# resid_gemm (wo, w2) epilogue: gate/x loads batched (8 gate loads once, x per token group double-buffered, counted vmcnt) instead of one vmcnt(0) round trip per 16 B
# speedup vs baseline: 1.0044x; 1.0044x over previous
; DI void phase_resid_gemm(const Prm& p, unsigned char* smem_raw, const u16* W, const u16* X, int K, const float* xsrc, float* xdst,
;                          const float* modl, int gtoff, int sb, int& base) {
;     ...
;     auto epi = [&](f32x4 (&acc)[2][2][4][2], int wr, int wc, int fr, int fq) __attribute__((always_inline)) {
; #pragma unroll
;       for (int bj = 0; bj < 2; ++bj)
; #pragma unroll
;         for (int n = 0; n < 2; ++n) {
;           const int tok = bcol + bj * 128 + wc * 32 + n * 16 + fr;
;           const float* gt = modl + condrow(sb, tok) * 6144 + gtoff;
; #pragma unroll
;           for (int ai = 0; ai < 2; ++ai)
; #pragma unroll
;             for (int m = 0; m < 4; ++m) {
;               const int nn = brow + ai * 128 + wr * 64 + m * 16 + fq * 4;
;               const f32x4 v = acc[ai][bj][m][n];
;               const float4 g4 = *(const float4*)(gt + nn);
;               const float4 xi = *(const float4*)(xsrc + (size_t)tok * 1024 + nn);
;               float4 o;
;               o.x = xi.x + g4.x * v[0]; o.y = xi.y + g4.y * v[1]; o.z = xi.z + g4.z * v[2]; o.w = xi.w + g4.w * v[3];
;               *(float4*)(xdst + (size_t)tok * 1024 + nn) = o;
;             }
;         }
;     };
.LBB0_2324:
	v_lshl_or_b32 v0, s66, 5, v141
	v_or_b32_e32 v132, s2, v0
	s_lshr_b32 s2, s63, 11
	s_lshl_b32 s3, s65, 6
	s_add_i32 s2, s56, s2
	v_lshl_or_b32 v130, v140, 2, s3
	s_mul_i32 s4, s2, 0x1800
	v_readlane_b32 s2, v254, 53
	v_readlane_b32 s3, v254, 54
	s_and_b64 s[2:3], s[2:3], exec
	s_cselect_b32 s2, 0, s4
	s_ashr_i32 s3, s2, 31
	v_ashrrev_i32_e32 v133, 31, v132
	v_add_u32_e32 v130, s5, v130
	v_readlane_b32 s4, v255, 13
	s_lshl_b64 s[2:3], s[2:3], 2
	v_ashrrev_i32_e32 v131, 31, v130
	v_lshlrev_b64 v[144:145], 12, v[132:133]
	v_readlane_b32 s5, v255, 14
	s_add_u32 s2, s55, s2
	v_lshlrev_b64 v[134:135], 2, v[130:131]
	v_lshl_add_u64 v[136:137], s[4:5], 0, v[144:145]
	s_addc_u32 s3, s58, s3
	v_lshl_add_u64 v[146:147], v[136:137], 0, v[134:135]
	v_lshl_add_u64 v[130:131], s[2:3], 0, v[134:135]
	global_load_dwordx4 v[148:151], v[130:131], off
	global_load_dwordx4 v[152:155], v[130:131], off offset:64
	global_load_dwordx4 v[156:159], v[130:131], off offset:128
	global_load_dwordx4 v[160:163], v[130:131], off offset:192
	global_load_dwordx4 v[164:167], v[130:131], off offset:512
	global_load_dwordx4 v[168:171], v[130:131], off offset:576
	global_load_dwordx4 v[172:175], v[130:131], off offset:640
	global_load_dwordx4 v[176:179], v[130:131], off offset:704
	global_load_dwordx4 v[180:183], v[146:147], off
	global_load_dwordx4 v[184:187], v[146:147], off offset:64
	global_load_dwordx4 v[188:191], v[146:147], off offset:128
	global_load_dwordx4 v[192:195], v[146:147], off offset:192
	global_load_dwordx4 v[196:199], v[146:147], off offset:512
	global_load_dwordx4 v[200:203], v[146:147], off offset:576
	global_load_dwordx4 v[204:207], v[146:147], off offset:640
	global_load_dwordx4 v[208:211], v[146:147], off offset:704
	v_readlane_b32 s2, v254, 41
	v_readlane_b32 s3, v254, 42
	v_readlane_b32 s84, v254, 31
	v_readlane_b32 s85, v254, 32
	v_lshl_add_u64 v[144:145], s[2:3], 0, v[144:145]
	v_lshl_add_u64 v[144:145], v[144:145], 0, v[134:135]
	s_add_i32 s61, s61, s30
	s_add_i32 s59, s59, s84
	s_add_i32 s60, s60, s57
	s_andn2_b64 vcc, exec, s[0:1]
	s_mov_b32 s56, s62
	v_readlane_b32 s88, v254, 35
	s_movk_i32 s86, 0x60
	s_movk_i32 s87, 0x1800
	s_mov_b32 s85, 0x800000
	s_movk_i32 s91, 0x3fff
	s_mov_b32 s90, 0x10000
	s_movk_i32 s65, 0x280
	s_mov_b64 s[10:11], 0x10000
	s_mov_b64 s[12:13], 0x80000
	s_mov_b64 s[14:15], 0x90000
	v_lshl_add_u64 v[132:133], v[146:147], 0, s[10:11]
	v_lshl_add_u64 v[134:135], v[146:147], 0, s[12:13]
	v_lshl_add_u64 v[140:141], v[146:147], 0, s[14:15]
	global_load_dwordx4 v[212:215], v[132:133], off
	global_load_dwordx4 v[216:219], v[132:133], off offset:64
	global_load_dwordx4 v[220:223], v[132:133], off offset:128
	global_load_dwordx4 v[226:229], v[132:133], off offset:192
	global_load_dwordx4 v[234:237], v[132:133], off offset:512
	global_load_dwordx4 v[244:247], v[132:133], off offset:576
	global_load_dwordx4 v[248:251], v[132:133], off offset:640
	global_load_dwordx4 v[136:139], v[132:133], off offset:704
	s_waitcnt vmcnt(8)
	v_pk_fma_f32 v[126:127], v[126:127], v[148:149], v[180:181]
	v_pk_fma_f32 v[128:129], v[128:129], v[150:151], v[182:183]
	v_pk_fma_f32 v[118:119], v[118:119], v[152:153], v[184:185]
	v_pk_fma_f32 v[120:121], v[120:121], v[154:155], v[186:187]
	v_pk_fma_f32 v[110:111], v[110:111], v[156:157], v[188:189]
	v_pk_fma_f32 v[112:113], v[112:113], v[158:159], v[190:191]
	v_pk_fma_f32 v[102:103], v[102:103], v[160:161], v[192:193]
	v_pk_fma_f32 v[104:105], v[104:105], v[162:163], v[194:195]
	v_pk_fma_f32 v[122:123], v[122:123], v[164:165], v[196:197]
	v_pk_fma_f32 v[124:125], v[124:125], v[166:167], v[198:199]
	v_pk_fma_f32 v[114:115], v[114:115], v[168:169], v[200:201]
	v_pk_fma_f32 v[116:117], v[116:117], v[170:171], v[202:203]
	v_pk_fma_f32 v[106:107], v[106:107], v[172:173], v[204:205]
	v_pk_fma_f32 v[108:109], v[108:109], v[174:175], v[206:207]
	v_pk_fma_f32 v[98:99], v[98:99], v[176:177], v[208:209]
	v_pk_fma_f32 v[100:101], v[100:101], v[178:179], v[210:211]
	global_load_dwordx4 v[180:183], v[134:135], off
	global_load_dwordx4 v[184:187], v[134:135], off offset:64
	global_load_dwordx4 v[188:191], v[134:135], off offset:128
	global_load_dwordx4 v[192:195], v[134:135], off offset:192
	global_load_dwordx4 v[196:199], v[134:135], off offset:512
	global_load_dwordx4 v[200:203], v[134:135], off offset:576
	global_load_dwordx4 v[204:207], v[134:135], off offset:640
	global_load_dwordx4 v[208:211], v[134:135], off offset:704
	global_store_dwordx4 v[144:145], v[126:129], off
	global_store_dwordx4 v[144:145], v[118:121], off offset:64
	global_store_dwordx4 v[144:145], v[110:113], off offset:128
	global_store_dwordx4 v[144:145], v[102:105], off offset:192
	global_store_dwordx4 v[144:145], v[122:125], off offset:512
	global_store_dwordx4 v[144:145], v[114:117], off offset:576
	global_store_dwordx4 v[144:145], v[106:109], off offset:640
	global_store_dwordx4 v[144:145], v[98:101], off offset:704
	s_waitcnt vmcnt(16)
; DI void phase_resid_gemm(const Prm& p, unsigned char* smem_raw, const u16* W, const u16* X, int K, const float* xsrc, float* xdst,
;                          const float* modl, int gtoff, int sb, int& base) {
;     ...
;     auto epi = [&](f32x4 (&acc)[2][2][4][2], int wr, int wc, int fr, int fq) __attribute__((always_inline)) {
; #pragma unroll
;       for (int bj = 0; bj < 2; ++bj)
; #pragma unroll
;         for (int n = 0; n < 2; ++n) {
;           const int tok = bcol + bj * 128 + wc * 32 + n * 16 + fr;
;           const float* gt = modl + condrow(sb, tok) * 6144 + gtoff;
; #pragma unroll
;           for (int ai = 0; ai < 2; ++ai)
; #pragma unroll
;             for (int m = 0; m < 4; ++m) {
;               const int nn = brow + ai * 128 + wr * 64 + m * 16 + fq * 4;
;               const f32x4 v = acc[ai][bj][m][n];
;               const float4 g4 = *(const float4*)(gt + nn);
;               const float4 xi = *(const float4*)(xsrc + (size_t)tok * 1024 + nn);
;               float4 o;
;               o.x = xi.x + g4.x * v[0]; o.y = xi.y + g4.y * v[1]; o.z = xi.z + g4.z * v[2]; o.w = xi.w + g4.w * v[3];
;               *(float4*)(xdst + (size_t)tok * 1024 + nn) = o;
;             }
;         }
;     };
	v_pk_fma_f32 v[94:95], v[94:95], v[148:149], v[212:213]
	v_pk_fma_f32 v[96:97], v[96:97], v[150:151], v[214:215]
	v_pk_fma_f32 v[86:87], v[86:87], v[152:153], v[216:217]
	v_pk_fma_f32 v[88:89], v[88:89], v[154:155], v[218:219]
	v_pk_fma_f32 v[78:79], v[78:79], v[156:157], v[220:221]
	v_pk_fma_f32 v[80:81], v[80:81], v[158:159], v[222:223]
	v_pk_fma_f32 v[70:71], v[70:71], v[160:161], v[226:227]
	v_pk_fma_f32 v[72:73], v[72:73], v[162:163], v[228:229]
	v_pk_fma_f32 v[90:91], v[90:91], v[164:165], v[234:235]
	v_pk_fma_f32 v[92:93], v[92:93], v[166:167], v[236:237]
	v_pk_fma_f32 v[82:83], v[82:83], v[168:169], v[244:245]
	v_pk_fma_f32 v[84:85], v[84:85], v[170:171], v[246:247]
	v_pk_fma_f32 v[74:75], v[74:75], v[172:173], v[248:249]
	v_pk_fma_f32 v[76:77], v[76:77], v[174:175], v[250:251]
	v_pk_fma_f32 v[66:67], v[66:67], v[176:177], v[136:137]
	v_pk_fma_f32 v[68:69], v[68:69], v[178:179], v[138:139]
	global_load_dwordx4 v[212:215], v[140:141], off
	global_load_dwordx4 v[216:219], v[140:141], off offset:64
	global_load_dwordx4 v[220:223], v[140:141], off offset:128
	global_load_dwordx4 v[226:229], v[140:141], off offset:192
	global_load_dwordx4 v[234:237], v[140:141], off offset:512
	global_load_dwordx4 v[244:247], v[140:141], off offset:576
	global_load_dwordx4 v[248:251], v[140:141], off offset:640
	global_load_dwordx4 v[136:139], v[140:141], off offset:704
	v_lshl_add_u64 v[130:131], v[144:145], 0, s[10:11]
	global_store_dwordx4 v[130:131], v[94:97], off
	global_store_dwordx4 v[130:131], v[86:89], off offset:64
	global_store_dwordx4 v[130:131], v[78:81], off offset:128
	global_store_dwordx4 v[130:131], v[70:73], off offset:192
	global_store_dwordx4 v[130:131], v[90:93], off offset:512
	global_store_dwordx4 v[130:131], v[82:85], off offset:576
	global_store_dwordx4 v[130:131], v[74:77], off offset:640
	global_store_dwordx4 v[130:131], v[66:69], off offset:704
	s_waitcnt vmcnt(24)
	v_pk_fma_f32 v[62:63], v[62:63], v[148:149], v[180:181]
	v_pk_fma_f32 v[64:65], v[64:65], v[150:151], v[182:183]
	v_pk_fma_f32 v[58:59], v[58:59], v[152:153], v[184:185]
	v_pk_fma_f32 v[60:61], v[60:61], v[154:155], v[186:187]
	v_pk_fma_f32 v[50:51], v[50:51], v[156:157], v[188:189]
	v_pk_fma_f32 v[52:53], v[52:53], v[158:159], v[190:191]
	v_pk_fma_f32 v[42:43], v[42:43], v[160:161], v[192:193]
	v_pk_fma_f32 v[44:45], v[44:45], v[162:163], v[194:195]
	v_pk_fma_f32 v[54:55], v[54:55], v[164:165], v[196:197]
	v_pk_fma_f32 v[56:57], v[56:57], v[166:167], v[198:199]
	v_pk_fma_f32 v[46:47], v[46:47], v[168:169], v[200:201]
	v_pk_fma_f32 v[48:49], v[48:49], v[170:171], v[202:203]
	v_pk_fma_f32 v[38:39], v[38:39], v[172:173], v[204:205]
	v_pk_fma_f32 v[40:41], v[40:41], v[174:175], v[206:207]
	v_pk_fma_f32 v[34:35], v[34:35], v[176:177], v[208:209]
	v_pk_fma_f32 v[36:37], v[36:37], v[178:179], v[210:211]
	v_lshl_add_u64 v[130:131], v[144:145], 0, s[12:13]
	global_store_dwordx4 v[130:131], v[62:65], off
	global_store_dwordx4 v[130:131], v[58:61], off offset:64
	global_store_dwordx4 v[130:131], v[50:53], off offset:128
	global_store_dwordx4 v[130:131], v[42:45], off offset:192
	global_store_dwordx4 v[130:131], v[54:57], off offset:512
	global_store_dwordx4 v[130:131], v[46:49], off offset:576
	global_store_dwordx4 v[130:131], v[38:41], off offset:640
	global_store_dwordx4 v[130:131], v[34:37], off offset:704
	s_waitcnt vmcnt(16)
	v_pk_fma_f32 v[30:31], v[30:31], v[148:149], v[212:213]
	v_pk_fma_f32 v[32:33], v[32:33], v[150:151], v[214:215]
	v_pk_fma_f32 v[26:27], v[26:27], v[152:153], v[216:217]
	v_pk_fma_f32 v[28:29], v[28:29], v[154:155], v[218:219]
	v_pk_fma_f32 v[18:19], v[18:19], v[156:157], v[220:221]
	v_pk_fma_f32 v[20:21], v[20:21], v[158:159], v[222:223]
	v_pk_fma_f32 v[10:11], v[10:11], v[160:161], v[226:227]
	v_pk_fma_f32 v[12:13], v[12:13], v[162:163], v[228:229]
	v_pk_fma_f32 v[22:23], v[22:23], v[164:165], v[234:235]
	v_pk_fma_f32 v[24:25], v[24:25], v[166:167], v[236:237]
	v_pk_fma_f32 v[14:15], v[14:15], v[168:169], v[244:245]
	v_pk_fma_f32 v[16:17], v[16:17], v[170:171], v[246:247]
	v_pk_fma_f32 v[6:7], v[6:7], v[172:173], v[248:249]
	v_pk_fma_f32 v[8:9], v[8:9], v[174:175], v[250:251]
	v_pk_fma_f32 v[2:3], v[2:3], v[176:177], v[136:137]
	v_pk_fma_f32 v[4:5], v[4:5], v[178:179], v[138:139]
	v_lshl_add_u64 v[130:131], v[144:145], 0, s[14:15]
	global_store_dwordx4 v[130:131], v[30:33], off
	global_store_dwordx4 v[130:131], v[26:29], off offset:64
	global_store_dwordx4 v[130:131], v[18:21], off offset:128
	global_store_dwordx4 v[130:131], v[10:13], off offset:192
	global_store_dwordx4 v[130:131], v[22:25], off offset:512
	global_store_dwordx4 v[130:131], v[14:17], off offset:576
	global_store_dwordx4 v[130:131], v[6:9], off offset:640
	global_store_dwordx4 v[130:131], v[2:5], off offset:704
	s_mov_b64 s[2:3], -1
	s_waitcnt lgkmcnt(0)
	s_barrier
	s_cbranch_vccz .LBB0_2337

; DI void phase_resid_gemm(const Prm& p, unsigned char* smem_raw, const u16* W, const u16* X, int K, const float* xsrc, float* xdst,
;                          const float* modl, int gtoff, int sb, int& base) {
;     ...
;     auto epi = [&](f32x4 (&acc)[2][2][4][2], int wr, int wc, int fr, int fq) __attribute__((always_inline)) {
; #pragma unroll
;       for (int bj = 0; bj < 2; ++bj)
; #pragma unroll
;         for (int n = 0; n < 2; ++n) {
;           const int tok = bcol + bj * 128 + wc * 32 + n * 16 + fr;
;           const float* gt = modl + condrow(sb, tok) * 6144 + gtoff;
; #pragma unroll
;           for (int ai = 0; ai < 2; ++ai)
; #pragma unroll
;             for (int m = 0; m < 4; ++m) {
;               const int nn = brow + ai * 128 + wr * 64 + m * 16 + fq * 4;
;               const f32x4 v = acc[ai][bj][m][n];
;               const float4 g4 = *(const float4*)(gt + nn);
;               const float4 xi = *(const float4*)(xsrc + (size_t)tok * 1024 + nn);
;               float4 o;
;               o.x = xi.x + g4.x * v[0]; o.y = xi.y + g4.y * v[1]; o.z = xi.z + g4.z * v[2]; o.w = xi.w + g4.w * v[3];
;               *(float4*)(xdst + (size_t)tok * 1024 + nn) = o;
;             }
;         }
;     };
.LBB0_2515:
	v_lshl_or_b32 v0, s66, 5, v141
	v_or_b32_e32 v132, s2, v0
	s_lshr_b32 s2, s63, 11
	s_lshl_b32 s3, s65, 6
	s_add_i32 s2, s8, s2
	v_lshl_or_b32 v130, v140, 2, s3
	s_mul_i32 s4, s2, 0x1800
	v_readlane_b32 s2, v254, 53
	v_readlane_b32 s3, v254, 54
	s_and_b64 s[2:3], s[2:3], exec
	s_cselect_b32 s2, 0, s4
	s_ashr_i32 s3, s2, 31
	s_lshl_b64 s[2:3], s[2:3], 2
	v_add_u32_e32 v130, s5, v130
	s_add_u32 s2, s55, s2
	v_ashrrev_i32_e32 v131, 31, v130
	s_addc_u32 s3, s58, s3
	v_lshlrev_b64 v[134:135], 2, v[130:131]
	v_ashrrev_i32_e32 v133, 31, v132
	v_lshl_add_u64 v[130:131], s[2:3], 0, v[134:135]
	v_readlane_b32 s2, v254, 41
	v_lshlrev_b64 v[136:137], 12, v[132:133]
	v_readlane_b32 s3, v254, 42
	v_readlane_b32 s84, v254, 31
	v_readlane_b32 s85, v254, 32
	v_lshl_add_u64 v[136:137], s[2:3], 0, v[136:137]
	v_lshl_add_u64 v[144:145], v[136:137], 0, v[134:135]
	global_load_dwordx4 v[148:151], v[130:131], off
	global_load_dwordx4 v[152:155], v[130:131], off offset:64
	global_load_dwordx4 v[156:159], v[130:131], off offset:128
	global_load_dwordx4 v[160:163], v[130:131], off offset:192
	global_load_dwordx4 v[164:167], v[130:131], off offset:512
	global_load_dwordx4 v[168:171], v[130:131], off offset:576
	global_load_dwordx4 v[172:175], v[130:131], off offset:640
	global_load_dwordx4 v[176:179], v[130:131], off offset:704
	global_load_dwordx4 v[180:183], v[144:145], off
	global_load_dwordx4 v[184:187], v[144:145], off offset:64
	global_load_dwordx4 v[188:191], v[144:145], off offset:128
	global_load_dwordx4 v[192:195], v[144:145], off offset:192
	global_load_dwordx4 v[196:199], v[144:145], off offset:512
	global_load_dwordx4 v[200:203], v[144:145], off offset:576
	global_load_dwordx4 v[204:207], v[144:145], off offset:640
	global_load_dwordx4 v[208:211], v[144:145], off offset:704
	s_add_i32 s61, s61, s30
	s_add_i32 s59, s59, s84
	s_add_i32 s60, s60, s9
	s_andn2_b64 vcc, exec, s[0:1]
	s_mov_b32 s56, s62
	v_readlane_b32 s88, v254, 35
	s_movk_i32 s86, 0x60
	s_movk_i32 s87, 0x1800
	s_mov_b32 s85, 0x800000
	s_movk_i32 s91, 0x3fff
	s_mov_b32 s90, 0x10000
	s_movk_i32 s65, 0x280
	s_mov_b64 s[10:11], 0x10000
	s_mov_b64 s[12:13], 0x80000
	s_mov_b64 s[14:15], 0x90000
	v_lshl_add_u64 v[132:133], v[144:145], 0, s[10:11]
	v_lshl_add_u64 v[134:135], v[144:145], 0, s[12:13]
	v_lshl_add_u64 v[140:141], v[144:145], 0, s[14:15]
	global_load_dwordx4 v[212:215], v[132:133], off
	global_load_dwordx4 v[216:219], v[132:133], off offset:64
	global_load_dwordx4 v[220:223], v[132:133], off offset:128
	global_load_dwordx4 v[226:229], v[132:133], off offset:192
	global_load_dwordx4 v[234:237], v[132:133], off offset:512
	global_load_dwordx4 v[244:247], v[132:133], off offset:576
	global_load_dwordx4 v[248:251], v[132:133], off offset:640
	global_load_dwordx4 v[136:139], v[132:133], off offset:704
	s_waitcnt vmcnt(8)
	v_pk_fma_f32 v[126:127], v[126:127], v[148:149], v[180:181]
	v_pk_fma_f32 v[128:129], v[128:129], v[150:151], v[182:183]
	v_pk_fma_f32 v[122:123], v[122:123], v[152:153], v[184:185]
	v_pk_fma_f32 v[124:125], v[124:125], v[154:155], v[186:187]
	v_pk_fma_f32 v[118:119], v[118:119], v[156:157], v[188:189]
	v_pk_fma_f32 v[120:121], v[120:121], v[158:159], v[190:191]
	v_pk_fma_f32 v[110:111], v[110:111], v[160:161], v[192:193]
	v_pk_fma_f32 v[112:113], v[112:113], v[162:163], v[194:195]
	v_pk_fma_f32 v[114:115], v[114:115], v[164:165], v[196:197]
	v_pk_fma_f32 v[116:117], v[116:117], v[166:167], v[198:199]
	v_pk_fma_f32 v[106:107], v[106:107], v[168:169], v[200:201]
	v_pk_fma_f32 v[108:109], v[108:109], v[170:171], v[202:203]
	v_pk_fma_f32 v[102:103], v[102:103], v[172:173], v[204:205]
	v_pk_fma_f32 v[104:105], v[104:105], v[174:175], v[206:207]
	v_pk_fma_f32 v[98:99], v[98:99], v[176:177], v[208:209]
	v_pk_fma_f32 v[100:101], v[100:101], v[178:179], v[210:211]
	global_load_dwordx4 v[180:183], v[134:135], off
	global_load_dwordx4 v[184:187], v[134:135], off offset:64
	global_load_dwordx4 v[188:191], v[134:135], off offset:128
	global_load_dwordx4 v[192:195], v[134:135], off offset:192
	global_load_dwordx4 v[196:199], v[134:135], off offset:512
	global_load_dwordx4 v[200:203], v[134:135], off offset:576
	global_load_dwordx4 v[204:207], v[134:135], off offset:640
	global_load_dwordx4 v[208:211], v[134:135], off offset:704
	global_store_dwordx4 v[144:145], v[126:129], off
	global_store_dwordx4 v[144:145], v[122:125], off offset:64
	global_store_dwordx4 v[144:145], v[118:121], off offset:128
	global_store_dwordx4 v[144:145], v[110:113], off offset:192
	global_store_dwordx4 v[144:145], v[114:117], off offset:512
	global_store_dwordx4 v[144:145], v[106:109], off offset:576
	global_store_dwordx4 v[144:145], v[102:105], off offset:640
	global_store_dwordx4 v[144:145], v[98:101], off offset:704
	s_waitcnt vmcnt(16)
; DI void phase_resid_gemm(const Prm& p, unsigned char* smem_raw, const u16* W, const u16* X, int K, const float* xsrc, float* xdst,
;                          const float* modl, int gtoff, int sb, int& base) {
;     ...
;     auto epi = [&](f32x4 (&acc)[2][2][4][2], int wr, int wc, int fr, int fq) __attribute__((always_inline)) {
; #pragma unroll
;       for (int bj = 0; bj < 2; ++bj)
; #pragma unroll
;         for (int n = 0; n < 2; ++n) {
;           const int tok = bcol + bj * 128 + wc * 32 + n * 16 + fr;
;           const float* gt = modl + condrow(sb, tok) * 6144 + gtoff;
; #pragma unroll
;           for (int ai = 0; ai < 2; ++ai)
; #pragma unroll
;             for (int m = 0; m < 4; ++m) {
;               const int nn = brow + ai * 128 + wr * 64 + m * 16 + fq * 4;
;               const f32x4 v = acc[ai][bj][m][n];
;               const float4 g4 = *(const float4*)(gt + nn);
;               const float4 xi = *(const float4*)(xsrc + (size_t)tok * 1024 + nn);
;               float4 o;
;               o.x = xi.x + g4.x * v[0]; o.y = xi.y + g4.y * v[1]; o.z = xi.z + g4.z * v[2]; o.w = xi.w + g4.w * v[3];
;               *(float4*)(xdst + (size_t)tok * 1024 + nn) = o;
;             }
;         }
;     };
	v_pk_fma_f32 v[94:95], v[94:95], v[148:149], v[212:213]
	v_pk_fma_f32 v[96:97], v[96:97], v[150:151], v[214:215]
	v_pk_fma_f32 v[90:91], v[90:91], v[152:153], v[216:217]
	v_pk_fma_f32 v[92:93], v[92:93], v[154:155], v[218:219]
	v_pk_fma_f32 v[86:87], v[86:87], v[156:157], v[220:221]
	v_pk_fma_f32 v[88:89], v[88:89], v[158:159], v[222:223]
	v_pk_fma_f32 v[78:79], v[78:79], v[160:161], v[226:227]
	v_pk_fma_f32 v[80:81], v[80:81], v[162:163], v[228:229]
	v_pk_fma_f32 v[82:83], v[82:83], v[164:165], v[234:235]
	v_pk_fma_f32 v[84:85], v[84:85], v[166:167], v[236:237]
	v_pk_fma_f32 v[74:75], v[74:75], v[168:169], v[244:245]
	v_pk_fma_f32 v[76:77], v[76:77], v[170:171], v[246:247]
	v_pk_fma_f32 v[70:71], v[70:71], v[172:173], v[248:249]
	v_pk_fma_f32 v[72:73], v[72:73], v[174:175], v[250:251]
	v_pk_fma_f32 v[66:67], v[66:67], v[176:177], v[136:137]
	v_pk_fma_f32 v[68:69], v[68:69], v[178:179], v[138:139]
	global_load_dwordx4 v[212:215], v[140:141], off
	global_load_dwordx4 v[216:219], v[140:141], off offset:64
	global_load_dwordx4 v[220:223], v[140:141], off offset:128
	global_load_dwordx4 v[226:229], v[140:141], off offset:192
	global_load_dwordx4 v[234:237], v[140:141], off offset:512
	global_load_dwordx4 v[244:247], v[140:141], off offset:576
	global_load_dwordx4 v[248:251], v[140:141], off offset:640
	global_load_dwordx4 v[136:139], v[140:141], off offset:704
	v_lshl_add_u64 v[130:131], v[144:145], 0, s[10:11]
	global_store_dwordx4 v[130:131], v[94:97], off
	global_store_dwordx4 v[130:131], v[90:93], off offset:64
	global_store_dwordx4 v[130:131], v[86:89], off offset:128
	global_store_dwordx4 v[130:131], v[78:81], off offset:192
	global_store_dwordx4 v[130:131], v[82:85], off offset:512
	global_store_dwordx4 v[130:131], v[74:77], off offset:576
	global_store_dwordx4 v[130:131], v[70:73], off offset:640
	global_store_dwordx4 v[130:131], v[66:69], off offset:704
	s_waitcnt vmcnt(24)
	v_pk_fma_f32 v[62:63], v[62:63], v[148:149], v[180:181]
	v_pk_fma_f32 v[64:65], v[64:65], v[150:151], v[182:183]
	v_pk_fma_f32 v[58:59], v[58:59], v[152:153], v[184:185]
	v_pk_fma_f32 v[60:61], v[60:61], v[154:155], v[186:187]
	v_pk_fma_f32 v[54:55], v[54:55], v[156:157], v[188:189]
	v_pk_fma_f32 v[56:57], v[56:57], v[158:159], v[190:191]
	v_pk_fma_f32 v[46:47], v[46:47], v[160:161], v[192:193]
	v_pk_fma_f32 v[48:49], v[48:49], v[162:163], v[194:195]
	v_pk_fma_f32 v[50:51], v[50:51], v[164:165], v[196:197]
	v_pk_fma_f32 v[52:53], v[52:53], v[166:167], v[198:199]
	v_pk_fma_f32 v[42:43], v[42:43], v[168:169], v[200:201]
	v_pk_fma_f32 v[44:45], v[44:45], v[170:171], v[202:203]
	v_pk_fma_f32 v[38:39], v[38:39], v[172:173], v[204:205]
	v_pk_fma_f32 v[40:41], v[40:41], v[174:175], v[206:207]
	v_pk_fma_f32 v[34:35], v[34:35], v[176:177], v[208:209]
	v_pk_fma_f32 v[36:37], v[36:37], v[178:179], v[210:211]
	v_lshl_add_u64 v[130:131], v[144:145], 0, s[12:13]
	global_store_dwordx4 v[130:131], v[62:65], off
	global_store_dwordx4 v[130:131], v[58:61], off offset:64
	global_store_dwordx4 v[130:131], v[54:57], off offset:128
	global_store_dwordx4 v[130:131], v[46:49], off offset:192
	global_store_dwordx4 v[130:131], v[50:53], off offset:512
	global_store_dwordx4 v[130:131], v[42:45], off offset:576
	global_store_dwordx4 v[130:131], v[38:41], off offset:640
	global_store_dwordx4 v[130:131], v[34:37], off offset:704
	s_waitcnt vmcnt(16)
	v_pk_fma_f32 v[30:31], v[30:31], v[148:149], v[212:213]
	v_pk_fma_f32 v[32:33], v[32:33], v[150:151], v[214:215]
	v_pk_fma_f32 v[26:27], v[26:27], v[152:153], v[216:217]
	v_pk_fma_f32 v[28:29], v[28:29], v[154:155], v[218:219]
	v_pk_fma_f32 v[22:23], v[22:23], v[156:157], v[220:221]
	v_pk_fma_f32 v[24:25], v[24:25], v[158:159], v[222:223]
	v_pk_fma_f32 v[14:15], v[14:15], v[160:161], v[226:227]
	v_pk_fma_f32 v[16:17], v[16:17], v[162:163], v[228:229]
	v_pk_fma_f32 v[18:19], v[18:19], v[164:165], v[234:235]
	v_pk_fma_f32 v[20:21], v[20:21], v[166:167], v[236:237]
	v_pk_fma_f32 v[10:11], v[10:11], v[168:169], v[244:245]
	v_pk_fma_f32 v[12:13], v[12:13], v[170:171], v[246:247]
	v_pk_fma_f32 v[6:7], v[6:7], v[172:173], v[248:249]
	v_pk_fma_f32 v[8:9], v[8:9], v[174:175], v[250:251]
	v_pk_fma_f32 v[2:3], v[2:3], v[176:177], v[136:137]
	v_pk_fma_f32 v[4:5], v[4:5], v[178:179], v[138:139]
	v_lshl_add_u64 v[130:131], v[144:145], 0, s[14:15]
	global_store_dwordx4 v[130:131], v[30:33], off
	global_store_dwordx4 v[130:131], v[26:29], off offset:64
	global_store_dwordx4 v[130:131], v[22:25], off offset:128
	global_store_dwordx4 v[130:131], v[14:17], off offset:192
	global_store_dwordx4 v[130:131], v[18:21], off offset:512
	global_store_dwordx4 v[130:131], v[10:13], off offset:576
	global_store_dwordx4 v[130:131], v[6:9], off offset:640
	global_store_dwordx4 v[130:131], v[2:5], off offset:704
	s_mov_b64 s[2:3], -1
	s_waitcnt lgkmcnt(0)
	s_barrier
	s_cbranch_vccz .LBB0_2528
